# attention steady loop: drop redundant max canonicalizations and +0 copies, fold DMA address constants into SALU adds (6.5 fewer VALU per wave-step)
# speedup vs baseline: 1.0038x; 1.0020x over previous
.LBB0_1989:
	s_lshl_b32 s20, s20, 1
	v_add_u32_e32 v0, s20, v251
	ds_read_b64_tr_b16 v[208:209], v0 offset:24576
	ds_read_b64_tr_b16 v[210:211], v0 offset:25088
	s_waitcnt lgkmcnt(9)
	v_mfma_f32_32x32x16_bf16 v[128:143], v[204:207], v[172:175], v[226:241]
	v_add_f32_e32 v2, v96, v97
	v_add_f32_e32 v2, v98, v2
	v_add_f32_e32 v2, v99, v2
	v_add_f32_e32 v2, v100, v2
	v_add_f32_e32 v2, v101, v2
	v_cvt_pk_bf16_f32 v160, v96, v97
	v_cvt_pk_bf16_f32 v161, v98, v99
	ds_read_b64_tr_b16 v[204:205], v0 offset:28672
	ds_read_b64_tr_b16 v[206:207], v0 offset:29184
	s_waitcnt lgkmcnt(10)
	v_mfma_f32_32x32x16_bf16 v[112:127], v[196:199], v[172:175], v[226:241]
	v_add_f32_e32 v2, v102, v2
	v_add_f32_e32 v2, v103, v2
	v_add_f32_e32 v2, v104, v2
	v_add_f32_e32 v2, v105, v2
	v_cvt_pk_bf16_f32 v162, v100, v101
	v_cvt_pk_bf16_f32 v163, v102, v103
	ds_read_b64_tr_b16 v[10:11], v0 offset:25600
	ds_read_b64_tr_b16 v[12:13], v0 offset:26112
	s_waitcnt lgkmcnt(11)
	v_mfma_f32_32x32x16_bf16 v[128:143], v[200:203], v[168:171], v[128:143]
	v_add_f32_e32 v2, v106, v2
	v_add_f32_e32 v2, v107, v2
	v_add_f32_e32 v2, v108, v2
	v_add_f32_e32 v2, v109, v2
	v_cvt_pk_bf16_f32 v152, v104, v105
	v_cvt_pk_bf16_f32 v153, v106, v107
	ds_read_b64_tr_b16 v[6:7], v0 offset:29696
	ds_read_b64_tr_b16 v[8:9], v0 offset:30208
	s_waitcnt lgkmcnt(12)
	v_mfma_f32_32x32x16_bf16 v[112:127], v[192:195], v[168:171], v[112:127]
	v_add_f32_e32 v2, v110, v2
	v_add_f32_e32 v2, v111, v2
	v_add_f32_e32 v2, v80, v2
	v_add_f32_e32 v14, v81, v2
	v_cvt_pk_bf16_f32 v154, v108, v109
	v_cvt_pk_bf16_f32 v155, v110, v111
	ds_read_b64_tr_b16 v[2:3], v0 offset:26624
	ds_read_b64_tr_b16 v[4:5], v0 offset:27136
	s_waitcnt lgkmcnt(13)
	v_mfma_f32_32x32x16_bf16 v[128:143], v[188:191], v[164:167], v[128:143]
	v_add_f32_e32 v14, v82, v14
	v_add_f32_e32 v14, v83, v14
	v_add_f32_e32 v14, v84, v14
	v_add_f32_e32 v14, v85, v14
	v_cvt_pk_bf16_f32 v148, v80, v81
	v_cvt_pk_bf16_f32 v149, v82, v83
	ds_read_b64_tr_b16 v[100:101], v0 offset:30720
	ds_read_b64_tr_b16 v[102:103], v0 offset:31232
	s_waitcnt lgkmcnt(14)
	v_mfma_f32_32x32x16_bf16 v[112:127], v[184:187], v[164:167], v[112:127]
	v_add_f32_e32 v14, v86, v14
	v_add_f32_e32 v14, v87, v14
	v_add_f32_e32 v14, v88, v14
	v_add_f32_e32 v14, v89, v14
	v_cvt_pk_bf16_f32 v150, v84, v85
	v_cvt_pk_bf16_f32 v151, v86, v87
	ds_read_b64_tr_b16 v[96:97], v0 offset:27648
	ds_read_b64_tr_b16 v[98:99], v0 offset:28160
	s_waitcnt lgkmcnt(14)
	v_mfma_f32_32x32x16_bf16 v[128:143], v[180:183], v[156:159], v[128:143]
	v_add_f32_e32 v14, v90, v14
	v_add_f32_e32 v14, v91, v14
	v_add_f32_e32 v14, v92, v14
	v_add_f32_e32 v14, v93, v14
	v_cvt_pk_bf16_f32 v144, v88, v89
	v_cvt_pk_bf16_f32 v145, v90, v91
	ds_read_b64_tr_b16 v[88:89], v0 offset:31744
	ds_read_b64_tr_b16 v[90:91], v0 offset:32256
	v_mfma_f32_32x32x16_bf16 v[112:127], v[176:179], v[156:159], v[112:127]
	v_add_f32_e32 v14, v94, v14
	v_add_f32_e32 v14, v95, v14
	v_add_f32_e32 v212, v247, v14
	v_cvt_pk_bf16_f32 v146, v92, v93
	v_cvt_pk_bf16_f32 v147, v94, v95
	s_add_u32 s30, s2, s78
	s_addc_u32 s31, s3, s79
	v_lshl_add_u64 v[80:81], v[220:221], 0, s[30:31]
	s_add_i32 s20, s29, s48


	s_mov_b32 s21, m0
	s_mov_b32 m0, s20
	s_nop 0
	global_load_lds_dwordx4 v[80:81], off
	s_mov_b32 m0, s21
	s_add_u32 s30, s2, 0x40000
	s_addc_u32 s31, s3, 0
	v_lshl_add_u64 v[80:81], v[222:223], 0, s[30:31]
	s_lshl_b32 s20, s27, 1

	s_add_i32 s21, s20, s49
	s_mov_b32 s24, m0
	s_mov_b32 m0, s21
	s_nop 0
	global_load_lds_dwordx4 v[80:81], off
	s_mov_b32 m0, s24
	v_lshl_add_u64 v[80:81], v[224:225], 0, s[30:31]
	s_add_i32 s20, s20, s50
	s_mov_b32 s21, m0
	s_mov_b32 m0, s20
	s_nop 0
	global_load_lds_dwordx4 v[80:81], off
	s_mov_b32 m0, s21
	v_max_f32_e32 v80, v128, v129


	v_max3_f32 v81, v130, v131, v113
	v_max3_f32 v80, v80, v112, v114
	v_max3_f32 v80, v80, v115, v132
	v_max3_f32 v81, v81, v134, v135
	v_max3_f32 v80, v80, v133, v116
	v_max3_f32 v81, v81, v118, v119
	v_max3_f32 v80, v80, v117, v136
	v_max3_f32 v81, v81, v138, v139
	v_max3_f32 v80, v80, v137, v120
	v_max3_f32 v81, v81, v122, v123
	v_max3_f32 v80, v80, v121, v140
	v_max3_f32 v81, v81, v142, v143
	v_max3_f32 v80, v80, v141, v124
	v_max3_f32 v81, v81, v126, v127
	v_max3_f32 v80, v80, v125, v81
	v_mov_b32_e32 v81, v80
	s_nop 1
	v_permlane32_swap_b32_e32 v80, v81
	v_max_f32_e32 v80, v80, v81


	s_mov_b32 s20, 0x41000000
	v_cmp_lt_f32_e32 vcc, s20, v80
	s_cmp_lg_u64 vcc, 0

	s_cselect_b64 s[20:21], -1, 0
	s_cbranch_vccnz .LBB0_1997

.LBB0_1992:
	s_add_i32 s20, s27, 0x2000
	s_cmpk_lg_i32 s27, 0x4000
	s_cselect_b32 s52, s20, 0
	s_lshl_b32 s20, s29, 1
	v_add_u32_e32 v208, s20, v251
	ds_read_b64_tr_b16 v[196:197], v208 offset:24576
	ds_read_b64_tr_b16 v[198:199], v208 offset:25088
	v_mfma_f32_32x32x16_bf16 v[96:111], v[84:87], v[172:175], v[226:241]
	v_add_f32_e32 v88, v128, v129
	v_add_f32_e32 v88, v130, v88
	v_add_f32_e32 v88, v131, v88
	v_add_f32_e32 v88, v132, v88
	v_add_f32_e32 v88, v133, v88
	v_cvt_pk_bf16_f32 v160, v128, v129
	v_cvt_pk_bf16_f32 v161, v130, v131
	ds_read_b64_tr_b16 v[192:193], v208 offset:28672
	ds_read_b64_tr_b16 v[194:195], v208 offset:29184
	v_add_f32_e32 v84, v134, v88
	v_add_f32_e32 v84, v135, v84
	v_add_f32_e32 v84, v136, v84
	v_add_f32_e32 v128, v137, v84
	v_mfma_f32_32x32x16_bf16 v[80:95], v[80:83], v[172:175], v[226:241]
	v_cvt_pk_bf16_f32 v162, v132, v133
	v_cvt_pk_bf16_f32 v163, v134, v135
	ds_read_b64_tr_b16 v[188:189], v208 offset:25600
	ds_read_b64_tr_b16 v[190:191], v208 offset:26112
	v_mfma_f32_32x32x16_bf16 v[96:111], v[184:187], v[168:171], v[96:111]
	v_add_f32_e32 v128, v138, v128
	v_add_f32_e32 v128, v139, v128
	v_add_f32_e32 v128, v140, v128
	v_add_f32_e32 v128, v141, v128
	v_cvt_pk_bf16_f32 v152, v136, v137
	v_cvt_pk_bf16_f32 v153, v138, v139
	ds_read_b64_tr_b16 v[136:137], v208 offset:29696
	ds_read_b64_tr_b16 v[138:139], v208 offset:30208
	v_mfma_f32_32x32x16_bf16 v[80:95], v[176:179], v[168:171], v[80:95]
	v_add_f32_e32 v128, v142, v128
	v_add_f32_e32 v128, v143, v128
	v_add_f32_e32 v128, v112, v128
	v_add_f32_e32 v128, v113, v128
	v_cvt_pk_bf16_f32 v154, v140, v141
	v_cvt_pk_bf16_f32 v155, v142, v143
	ds_read_b64_tr_b16 v[132:133], v208 offset:26624
	ds_read_b64_tr_b16 v[134:135], v208 offset:27136
	v_mfma_f32_32x32x16_bf16 v[96:111], v[180:183], v[164:167], v[96:111]
	v_add_f32_e32 v128, v114, v128
	v_add_f32_e32 v128, v115, v128
	v_add_f32_e32 v128, v116, v128
	v_add_f32_e32 v140, v117, v128
	v_cvt_pk_bf16_f32 v148, v112, v113
	v_cvt_pk_bf16_f32 v149, v114, v115
	ds_read_b64_tr_b16 v[128:129], v208 offset:30720
	ds_read_b64_tr_b16 v[130:131], v208 offset:31232
	v_mfma_f32_32x32x16_bf16 v[80:95], v[6:9], v[164:167], v[80:95]
	v_add_f32_e32 v6, v118, v140
	v_add_f32_e32 v6, v119, v6
	v_add_f32_e32 v6, v120, v6
	v_add_f32_e32 v6, v121, v6
	v_cvt_pk_bf16_f32 v150, v116, v117
	v_cvt_pk_bf16_f32 v151, v118, v119
	ds_read_b64_tr_b16 v[112:113], v208 offset:27648
	ds_read_b64_tr_b16 v[114:115], v208 offset:28160
	v_mfma_f32_32x32x16_bf16 v[96:111], v[10:13], v[156:159], v[96:111]
	v_add_f32_e32 v6, v122, v6
	v_add_f32_e32 v6, v123, v6
	v_add_f32_e32 v6, v124, v6
	v_add_f32_e32 v10, v125, v6
	v_cvt_pk_bf16_f32 v144, v120, v121
	v_cvt_pk_bf16_f32 v145, v122, v123
	ds_read_b64_tr_b16 v[6:7], v208 offset:31744
	ds_read_b64_tr_b16 v[8:9], v208 offset:32256
	v_mfma_f32_32x32x16_bf16 v[80:95], v[2:5], v[156:159], v[80:95]
	v_add_f32_e32 v2, v126, v10
	v_add_f32_e32 v2, v127, v2
	v_add_f32_e32 v247, v212, v2
	v_cvt_pk_bf16_f32 v146, v124, v125
	v_cvt_pk_bf16_f32 v147, v126, v127
	s_add_u32 s20, s2, 0xa0000
	s_addc_u32 s21, s3, 0
	v_lshl_add_u64 v[2:3], v[220:221], 0, s[20:21]
	s_add_i32 s20, s27, s48
	s_mov_b32 s21, m0
	s_mov_b32 m0, s20
	s_nop 0
	global_load_lds_dwordx4 v[2:3], off
	s_mov_b32 m0, s21
	s_add_u32 s30, s2, s56
	s_addc_u32 s31, s3, s57
	v_lshl_add_u64 v[2:3], v[222:223], 0, s[30:31]
	s_lshl_b32 s20, s52, 1
	s_add_i32 s21, s20, s49
	s_mov_b32 s24, m0
	s_mov_b32 m0, s21
	s_nop 0
	global_load_lds_dwordx4 v[2:3], off
	s_mov_b32 m0, s24
	v_lshl_add_u64 v[2:3], v[224:225], 0, s[30:31]
	s_add_i32 s20, s20, s50
	s_mov_b32 s21, m0
	s_mov_b32 m0, s20
	s_nop 0
	global_load_lds_dwordx4 v[2:3], off
	s_mov_b32 m0, s21
	v_max_f32_e32 v2, v96, v97


	v_max3_f32 v3, v98, v99, v81
	v_max3_f32 v2, v2, v80, v82
	v_max3_f32 v2, v2, v83, v100
	v_max3_f32 v3, v3, v102, v103
	v_max3_f32 v2, v2, v101, v84
	v_max3_f32 v3, v3, v86, v87
	v_max3_f32 v2, v2, v85, v104
	v_max3_f32 v3, v3, v106, v107
	v_max3_f32 v2, v2, v105, v88
	v_max3_f32 v3, v3, v90, v91
	v_max3_f32 v2, v2, v89, v108
	v_max3_f32 v3, v3, v110, v111
	v_max3_f32 v2, v2, v109, v92
	v_max3_f32 v3, v3, v94, v95
	v_max3_f32 v2, v2, v93, v3
	v_mov_b32_e32 v3, v2
	s_nop 1
	v_permlane32_swap_b32_e32 v2, v3
	v_max_f32_e32 v2, v2, v3


	s_mov_b32 s20, 0x41000000
	v_cmp_lt_f32_e32 vcc, s20, v2
	s_cmp_lg_u64 vcc, 0

	s_cselect_b64 s[20:21], -1, 0
	s_cbranch_vccnz .LBB0_2000
